# diff attention main path: dropped the wait states after QK (first dependent VALU read is 15+ instructions later)
# baseline (speedup 1.0000x reference)
.LBB0_790:
	s_sub_i32 s73, s56, 158
	s_cmp_gt_i32 s73, s4
	s_cbranch_scc1 .Ld16a_end0
	s_cmp_eq_u32 s57, 2
	s_cbranch_scc1 .Ld16a_rd0
	ds_read_b128 v[252:255], v219 offset:128
	s_waitcnt lgkmcnt(3)
	v_mfma_f32_16x16x32_bf16 v[130:133], v[238:241], v[162:165], 0
	v_mfma_f32_16x16x32_bf16 v[146:149], v[238:241], v[178:181], 0
	ds_read_b128 v[238:241], v218 offset:4096
	s_waitcnt lgkmcnt(3)
	v_mfma_f32_16x16x32_bf16 v[130:133], v[242:245], v[166:169], v[130:133]
	v_mfma_f32_16x16x32_bf16 v[146:149], v[242:245], v[182:185], v[146:149]
	ds_read_b128 v[242:245], v219 offset:4096
	s_waitcnt lgkmcnt(3)
	v_mfma_f32_16x16x32_bf16 v[130:133], v[246:249], v[170:173], v[130:133]
	v_mfma_f32_16x16x32_bf16 v[146:149], v[246:249], v[186:189], v[146:149]
	ds_read_b128 v[246:249], v218 offset:4224
	s_waitcnt lgkmcnt(3)
	v_mfma_f32_16x16x32_bf16 v[130:133], v[252:255], v[174:177], v[130:133]
	v_mfma_f32_16x16x32_bf16 v[146:149], v[252:255], v[190:193], v[146:149]
	ds_read_b128 v[252:255], v219 offset:4224
	s_waitcnt lgkmcnt(3)
	v_mfma_f32_16x16x32_bf16 v[134:137], v[238:241], v[162:165], 0
	v_mfma_f32_16x16x32_bf16 v[150:153], v[238:241], v[178:181], 0
	ds_read_b128 v[238:241], v218 offset:8192
	s_waitcnt lgkmcnt(3)
	v_mfma_f32_16x16x32_bf16 v[134:137], v[242:245], v[166:169], v[134:137]
	v_mfma_f32_16x16x32_bf16 v[150:153], v[242:245], v[182:185], v[150:153]
	ds_read_b128 v[242:245], v219 offset:8192
	s_waitcnt lgkmcnt(3)
	v_mfma_f32_16x16x32_bf16 v[134:137], v[246:249], v[170:173], v[134:137]
	v_mfma_f32_16x16x32_bf16 v[150:153], v[246:249], v[186:189], v[150:153]
	ds_read_b128 v[246:249], v218 offset:8320
	s_waitcnt lgkmcnt(3)
	v_mfma_f32_16x16x32_bf16 v[134:137], v[252:255], v[174:177], v[134:137]
	v_mfma_f32_16x16x32_bf16 v[150:153], v[252:255], v[190:193], v[150:153]
	ds_read_b128 v[252:255], v219 offset:8320
	s_waitcnt lgkmcnt(3)
	v_mfma_f32_16x16x32_bf16 v[138:141], v[238:241], v[162:165], 0
	v_mfma_f32_16x16x32_bf16 v[154:157], v[238:241], v[178:181], 0
	ds_read_b128 v[238:241], v218 offset:12288
	s_waitcnt lgkmcnt(3)
	v_mfma_f32_16x16x32_bf16 v[138:141], v[242:245], v[166:169], v[138:141]
	v_mfma_f32_16x16x32_bf16 v[154:157], v[242:245], v[182:185], v[154:157]
	ds_read_b128 v[242:245], v219 offset:12288
	s_waitcnt lgkmcnt(3)
	v_mfma_f32_16x16x32_bf16 v[138:141], v[246:249], v[170:173], v[138:141]
	v_mfma_f32_16x16x32_bf16 v[154:157], v[246:249], v[186:189], v[154:157]
	ds_read_b128 v[246:249], v218 offset:12416
	s_waitcnt lgkmcnt(3)
	v_mfma_f32_16x16x32_bf16 v[138:141], v[252:255], v[174:177], v[138:141]
	v_mfma_f32_16x16x32_bf16 v[154:157], v[252:255], v[190:193], v[154:157]
	ds_read_b128 v[252:255], v219 offset:12416
	s_waitcnt lgkmcnt(3)
	v_mfma_f32_16x16x32_bf16 v[142:145], v[238:241], v[162:165], 0
	v_mfma_f32_16x16x32_bf16 v[158:161], v[238:241], v[178:181], 0
	s_waitcnt lgkmcnt(2)
	v_mfma_f32_16x16x32_bf16 v[142:145], v[242:245], v[166:169], v[142:145]
	v_mfma_f32_16x16x32_bf16 v[158:161], v[242:245], v[182:185], v[158:161]
	s_waitcnt lgkmcnt(1)
	v_mfma_f32_16x16x32_bf16 v[142:145], v[246:249], v[170:173], v[142:145]
	v_mfma_f32_16x16x32_bf16 v[158:161], v[246:249], v[186:189], v[158:161]
	s_waitcnt lgkmcnt(0)
	v_mfma_f32_16x16x32_bf16 v[142:145], v[252:255], v[174:177], v[142:145]
	v_mfma_f32_16x16x32_bf16 v[158:161], v[252:255], v[190:193], v[158:161]
	s_sub_i32 s36, s56, 64
	s_cmp_le_i32 s36, s4
	s_cbranch_scc1 .Ld16a_nma0
	v_cmp_gt_i32_e64 s[74:75], 0, v233
	v_cmp_gt_i32_e64 s[76:77], 1, v233
	v_cmp_gt_i32_e64 s[78:79], 2, v233
	v_cmp_gt_i32_e64 s[80:81], 3, v233
	v_cndmask_b32_e64 v130, v130, v230, s[74:75]
	v_cndmask_b32_e64 v131, v131, v230, s[76:77]
	v_cndmask_b32_e64 v132, v132, v230, s[78:79]
	v_cndmask_b32_e64 v133, v133, v230, s[80:81]
	v_cmp_gt_i32_e64 s[74:75], 16, v233
	v_cmp_gt_i32_e64 s[76:77], 17, v233
	v_cmp_gt_i32_e64 s[78:79], 18, v233
	v_cmp_gt_i32_e64 s[80:81], 19, v233
	v_cndmask_b32_e64 v134, v134, v230, s[74:75]
	v_cndmask_b32_e64 v135, v135, v230, s[76:77]
	v_cndmask_b32_e64 v136, v136, v230, s[78:79]
	v_cndmask_b32_e64 v137, v137, v230, s[80:81]
	v_cmp_gt_i32_e64 s[74:75], 32, v233
	v_cmp_gt_i32_e64 s[76:77], 33, v233
	v_cmp_gt_i32_e64 s[78:79], 34, v233
	v_cmp_gt_i32_e64 s[80:81], 35, v233
	v_cndmask_b32_e64 v138, v138, v230, s[74:75]
	v_cndmask_b32_e64 v139, v139, v230, s[76:77]
	v_cndmask_b32_e64 v140, v140, v230, s[78:79]
	v_cndmask_b32_e64 v141, v141, v230, s[80:81]
	v_cmp_gt_i32_e64 s[74:75], 48, v233
	v_cmp_gt_i32_e64 s[76:77], 49, v233
	v_cmp_gt_i32_e64 s[78:79], 50, v233
	v_cmp_gt_i32_e64 s[80:81], 51, v233
	v_cndmask_b32_e64 v142, v142, v230, s[74:75]
	v_cndmask_b32_e64 v143, v143, v230, s[76:77]
	v_cndmask_b32_e64 v144, v144, v230, s[78:79]
	v_cndmask_b32_e64 v145, v145, v230, s[80:81]
	v_cmp_gt_i32_e64 s[74:75], -16, v233
	v_cmp_gt_i32_e64 s[76:77], -15, v233
	v_cmp_gt_i32_e64 s[78:79], -14, v233
	v_cmp_gt_i32_e64 s[80:81], -13, v233
	v_cndmask_b32_e64 v146, v146, v230, s[74:75]
	v_cndmask_b32_e64 v147, v147, v230, s[76:77]
	v_cndmask_b32_e64 v148, v148, v230, s[78:79]
	v_cndmask_b32_e64 v149, v149, v230, s[80:81]
	v_cmp_gt_i32_e64 s[74:75], 0, v233
	v_cmp_gt_i32_e64 s[76:77], 1, v233
	v_cmp_gt_i32_e64 s[78:79], 2, v233
	v_cmp_gt_i32_e64 s[80:81], 3, v233
	v_cndmask_b32_e64 v150, v150, v230, s[74:75]
	v_cndmask_b32_e64 v151, v151, v230, s[76:77]
	v_cndmask_b32_e64 v152, v152, v230, s[78:79]
	v_cndmask_b32_e64 v153, v153, v230, s[80:81]
	v_cmp_gt_i32_e64 s[74:75], 16, v233
	v_cmp_gt_i32_e64 s[76:77], 17, v233
	v_cmp_gt_i32_e64 s[78:79], 18, v233
	v_cmp_gt_i32_e64 s[80:81], 19, v233
	v_cndmask_b32_e64 v154, v154, v230, s[74:75]
	v_cndmask_b32_e64 v155, v155, v230, s[76:77]
	v_cndmask_b32_e64 v156, v156, v230, s[78:79]
	v_cndmask_b32_e64 v157, v157, v230, s[80:81]
	v_cmp_gt_i32_e64 s[74:75], 32, v233
	v_cmp_gt_i32_e64 s[76:77], 33, v233
	v_cmp_gt_i32_e64 s[78:79], 34, v233
	v_cmp_gt_i32_e64 s[80:81], 35, v233
	v_cndmask_b32_e64 v158, v158, v230, s[74:75]
	v_cndmask_b32_e64 v159, v159, v230, s[76:77]
	v_cndmask_b32_e64 v160, v160, v230, s[78:79]
	v_cndmask_b32_e64 v161, v161, v230, s[80:81]

.LBB0_798:
	s_sub_i32 s73, s56, 94
	s_cmp_gt_i32 s73, s4
	s_cbranch_scc1 .Ld16a_end1
	ds_read_b128 v[252:255], v219 offset:16512
	s_waitcnt lgkmcnt(3)
	v_mfma_f32_16x16x32_bf16 v[130:133], v[238:241], v[162:165], 0
	v_mfma_f32_16x16x32_bf16 v[146:149], v[238:241], v[178:181], 0
	ds_read_b128 v[238:241], v218 offset:20480
	s_waitcnt lgkmcnt(3)
	v_mfma_f32_16x16x32_bf16 v[130:133], v[242:245], v[166:169], v[130:133]
	v_mfma_f32_16x16x32_bf16 v[146:149], v[242:245], v[182:185], v[146:149]
	ds_read_b128 v[242:245], v219 offset:20480
	s_waitcnt lgkmcnt(3)
	v_mfma_f32_16x16x32_bf16 v[130:133], v[246:249], v[170:173], v[130:133]
	v_mfma_f32_16x16x32_bf16 v[146:149], v[246:249], v[186:189], v[146:149]
	ds_read_b128 v[246:249], v218 offset:20608
	s_waitcnt lgkmcnt(3)
	v_mfma_f32_16x16x32_bf16 v[130:133], v[252:255], v[174:177], v[130:133]
	v_mfma_f32_16x16x32_bf16 v[146:149], v[252:255], v[190:193], v[146:149]
	ds_read_b128 v[252:255], v219 offset:20608
	s_waitcnt lgkmcnt(3)
	v_mfma_f32_16x16x32_bf16 v[134:137], v[238:241], v[162:165], 0
	v_mfma_f32_16x16x32_bf16 v[150:153], v[238:241], v[178:181], 0
	ds_read_b128 v[238:241], v218 offset:24576
	s_waitcnt lgkmcnt(3)
	v_mfma_f32_16x16x32_bf16 v[134:137], v[242:245], v[166:169], v[134:137]
	v_mfma_f32_16x16x32_bf16 v[150:153], v[242:245], v[182:185], v[150:153]
	ds_read_b128 v[242:245], v219 offset:24576
	s_waitcnt lgkmcnt(3)
	v_mfma_f32_16x16x32_bf16 v[134:137], v[246:249], v[170:173], v[134:137]
	v_mfma_f32_16x16x32_bf16 v[150:153], v[246:249], v[186:189], v[150:153]
	ds_read_b128 v[246:249], v218 offset:24704
	s_waitcnt lgkmcnt(3)
	v_mfma_f32_16x16x32_bf16 v[134:137], v[252:255], v[174:177], v[134:137]
	v_mfma_f32_16x16x32_bf16 v[150:153], v[252:255], v[190:193], v[150:153]
	ds_read_b128 v[252:255], v219 offset:24704
	s_waitcnt lgkmcnt(3)
	v_mfma_f32_16x16x32_bf16 v[138:141], v[238:241], v[162:165], 0
	v_mfma_f32_16x16x32_bf16 v[154:157], v[238:241], v[178:181], 0
	ds_read_b128 v[238:241], v218 offset:28672
	s_waitcnt lgkmcnt(3)
	v_mfma_f32_16x16x32_bf16 v[138:141], v[242:245], v[166:169], v[138:141]
	v_mfma_f32_16x16x32_bf16 v[154:157], v[242:245], v[182:185], v[154:157]
	ds_read_b128 v[242:245], v219 offset:28672
	s_waitcnt lgkmcnt(3)
	v_mfma_f32_16x16x32_bf16 v[138:141], v[246:249], v[170:173], v[138:141]
	v_mfma_f32_16x16x32_bf16 v[154:157], v[246:249], v[186:189], v[154:157]
	ds_read_b128 v[246:249], v218 offset:28800
	s_waitcnt lgkmcnt(3)
	v_mfma_f32_16x16x32_bf16 v[138:141], v[252:255], v[174:177], v[138:141]
	v_mfma_f32_16x16x32_bf16 v[154:157], v[252:255], v[190:193], v[154:157]
	ds_read_b128 v[252:255], v219 offset:28800
	s_waitcnt lgkmcnt(3)
	v_mfma_f32_16x16x32_bf16 v[142:145], v[238:241], v[162:165], 0
	v_mfma_f32_16x16x32_bf16 v[158:161], v[238:241], v[178:181], 0
	s_waitcnt lgkmcnt(2)
	v_mfma_f32_16x16x32_bf16 v[142:145], v[242:245], v[166:169], v[142:145]
	v_mfma_f32_16x16x32_bf16 v[158:161], v[242:245], v[182:185], v[158:161]
	s_waitcnt lgkmcnt(1)
	v_mfma_f32_16x16x32_bf16 v[142:145], v[246:249], v[170:173], v[142:145]
	v_mfma_f32_16x16x32_bf16 v[158:161], v[246:249], v[186:189], v[158:161]
	s_waitcnt lgkmcnt(0)
	v_mfma_f32_16x16x32_bf16 v[142:145], v[252:255], v[174:177], v[142:145]
	v_mfma_f32_16x16x32_bf16 v[158:161], v[252:255], v[190:193], v[158:161]
	s_cmp_le_i32 s56, s4
	s_cbranch_scc1 .Ld16a_nma1
	v_subrev_u32_e32 v246, 64, v233
	v_cmp_gt_i32_e64 s[74:75], 0, v246
	v_cmp_gt_i32_e64 s[76:77], 1, v246
	v_cmp_gt_i32_e64 s[78:79], 2, v246
	v_cmp_gt_i32_e64 s[80:81], 3, v246
	v_cndmask_b32_e64 v130, v130, v230, s[74:75]
	v_cndmask_b32_e64 v131, v131, v230, s[76:77]
	v_cndmask_b32_e64 v132, v132, v230, s[78:79]
	v_cndmask_b32_e64 v133, v133, v230, s[80:81]
	v_cmp_gt_i32_e64 s[74:75], 16, v246
	v_cmp_gt_i32_e64 s[76:77], 17, v246
	v_cmp_gt_i32_e64 s[78:79], 18, v246
	v_cmp_gt_i32_e64 s[80:81], 19, v246
	v_cndmask_b32_e64 v134, v134, v230, s[74:75]
	v_cndmask_b32_e64 v135, v135, v230, s[76:77]
	v_cndmask_b32_e64 v136, v136, v230, s[78:79]
	v_cndmask_b32_e64 v137, v137, v230, s[80:81]
	v_cmp_gt_i32_e64 s[74:75], 32, v246
	v_cmp_gt_i32_e64 s[76:77], 33, v246
	v_cmp_gt_i32_e64 s[78:79], 34, v246
	v_cmp_gt_i32_e64 s[80:81], 35, v246
	v_cndmask_b32_e64 v138, v138, v230, s[74:75]
	v_cndmask_b32_e64 v139, v139, v230, s[76:77]
	v_cndmask_b32_e64 v140, v140, v230, s[78:79]
	v_cndmask_b32_e64 v141, v141, v230, s[80:81]
	v_cmp_gt_i32_e64 s[74:75], 48, v246
	v_cmp_gt_i32_e64 s[76:77], 49, v246
	v_cmp_gt_i32_e64 s[78:79], 50, v246
	v_cmp_gt_i32_e64 s[80:81], 51, v246
	v_cndmask_b32_e64 v142, v142, v230, s[74:75]
	v_cndmask_b32_e64 v143, v143, v230, s[76:77]
	v_cndmask_b32_e64 v144, v144, v230, s[78:79]
	v_cndmask_b32_e64 v145, v145, v230, s[80:81]
	v_cmp_gt_i32_e64 s[74:75], -16, v246
	v_cmp_gt_i32_e64 s[76:77], -15, v246
	v_cmp_gt_i32_e64 s[78:79], -14, v246
	v_cmp_gt_i32_e64 s[80:81], -13, v246
	v_cndmask_b32_e64 v146, v146, v230, s[74:75]
	v_cndmask_b32_e64 v147, v147, v230, s[76:77]
	v_cndmask_b32_e64 v148, v148, v230, s[78:79]
	v_cndmask_b32_e64 v149, v149, v230, s[80:81]
	v_cmp_gt_i32_e64 s[74:75], 0, v246
	v_cmp_gt_i32_e64 s[76:77], 1, v246
	v_cmp_gt_i32_e64 s[78:79], 2, v246
	v_cmp_gt_i32_e64 s[80:81], 3, v246
	v_cndmask_b32_e64 v150, v150, v230, s[74:75]
	v_cndmask_b32_e64 v151, v151, v230, s[76:77]
	v_cndmask_b32_e64 v152, v152, v230, s[78:79]
	v_cndmask_b32_e64 v153, v153, v230, s[80:81]
	v_cmp_gt_i32_e64 s[74:75], 16, v246
	v_cmp_gt_i32_e64 s[76:77], 17, v246
	v_cmp_gt_i32_e64 s[78:79], 18, v246
	v_cmp_gt_i32_e64 s[80:81], 19, v246
	v_cndmask_b32_e64 v154, v154, v230, s[74:75]
	v_cndmask_b32_e64 v155, v155, v230, s[76:77]
	v_cndmask_b32_e64 v156, v156, v230, s[78:79]
	v_cndmask_b32_e64 v157, v157, v230, s[80:81]
	v_cmp_gt_i32_e64 s[74:75], 32, v246
	v_cmp_gt_i32_e64 s[76:77], 33, v246
	v_cmp_gt_i32_e64 s[78:79], 34, v246
	v_cmp_gt_i32_e64 s[80:81], 35, v246
	v_cndmask_b32_e64 v158, v158, v230, s[74:75]
	v_cndmask_b32_e64 v159, v159, v230, s[76:77]
	v_cndmask_b32_e64 v160, v160, v230, s[78:79]
	v_cndmask_b32_e64 v161, v161, v230, s[80:81]

.LBB0_2410:
	s_sub_i32 s73, s60, 158
	s_cmp_gt_i32 s73, s4
	s_cbranch_scc1 .Ld16c_end0
	s_cmp_eq_u32 s61, 2
	s_cbranch_scc1 .Ld16c_rd0
	ds_read_b128 v[252:255], v219 offset:128
	s_waitcnt lgkmcnt(3)
	v_mfma_f32_16x16x32_bf16 v[130:133], v[238:241], v[162:165], 0
	v_mfma_f32_16x16x32_bf16 v[146:149], v[238:241], v[178:181], 0
	ds_read_b128 v[238:241], v218 offset:4096
	s_waitcnt lgkmcnt(3)
	v_mfma_f32_16x16x32_bf16 v[130:133], v[242:245], v[166:169], v[130:133]
	v_mfma_f32_16x16x32_bf16 v[146:149], v[242:245], v[182:185], v[146:149]
	ds_read_b128 v[242:245], v219 offset:4096
	s_waitcnt lgkmcnt(3)
	v_mfma_f32_16x16x32_bf16 v[130:133], v[246:249], v[170:173], v[130:133]
	v_mfma_f32_16x16x32_bf16 v[146:149], v[246:249], v[186:189], v[146:149]
	ds_read_b128 v[246:249], v218 offset:4224
	s_waitcnt lgkmcnt(3)
	v_mfma_f32_16x16x32_bf16 v[130:133], v[252:255], v[174:177], v[130:133]
	v_mfma_f32_16x16x32_bf16 v[146:149], v[252:255], v[190:193], v[146:149]
	ds_read_b128 v[252:255], v219 offset:4224
	s_waitcnt lgkmcnt(3)
	v_mfma_f32_16x16x32_bf16 v[134:137], v[238:241], v[162:165], 0
	v_mfma_f32_16x16x32_bf16 v[150:153], v[238:241], v[178:181], 0
	ds_read_b128 v[238:241], v218 offset:8192
	s_waitcnt lgkmcnt(3)
	v_mfma_f32_16x16x32_bf16 v[134:137], v[242:245], v[166:169], v[134:137]
	v_mfma_f32_16x16x32_bf16 v[150:153], v[242:245], v[182:185], v[150:153]
	ds_read_b128 v[242:245], v219 offset:8192
	s_waitcnt lgkmcnt(3)
	v_mfma_f32_16x16x32_bf16 v[134:137], v[246:249], v[170:173], v[134:137]
	v_mfma_f32_16x16x32_bf16 v[150:153], v[246:249], v[186:189], v[150:153]
	ds_read_b128 v[246:249], v218 offset:8320
	s_waitcnt lgkmcnt(3)
	v_mfma_f32_16x16x32_bf16 v[134:137], v[252:255], v[174:177], v[134:137]
	v_mfma_f32_16x16x32_bf16 v[150:153], v[252:255], v[190:193], v[150:153]
	ds_read_b128 v[252:255], v219 offset:8320
	s_waitcnt lgkmcnt(3)
	v_mfma_f32_16x16x32_bf16 v[138:141], v[238:241], v[162:165], 0
	v_mfma_f32_16x16x32_bf16 v[154:157], v[238:241], v[178:181], 0
	ds_read_b128 v[238:241], v218 offset:12288
	s_waitcnt lgkmcnt(3)
	v_mfma_f32_16x16x32_bf16 v[138:141], v[242:245], v[166:169], v[138:141]
	v_mfma_f32_16x16x32_bf16 v[154:157], v[242:245], v[182:185], v[154:157]
	ds_read_b128 v[242:245], v219 offset:12288
	s_waitcnt lgkmcnt(3)
	v_mfma_f32_16x16x32_bf16 v[138:141], v[246:249], v[170:173], v[138:141]
	v_mfma_f32_16x16x32_bf16 v[154:157], v[246:249], v[186:189], v[154:157]
	ds_read_b128 v[246:249], v218 offset:12416
	s_waitcnt lgkmcnt(3)
	v_mfma_f32_16x16x32_bf16 v[138:141], v[252:255], v[174:177], v[138:141]
	v_mfma_f32_16x16x32_bf16 v[154:157], v[252:255], v[190:193], v[154:157]
	ds_read_b128 v[252:255], v219 offset:12416
	s_waitcnt lgkmcnt(3)
	v_mfma_f32_16x16x32_bf16 v[142:145], v[238:241], v[162:165], 0
	v_mfma_f32_16x16x32_bf16 v[158:161], v[238:241], v[178:181], 0
	s_waitcnt lgkmcnt(2)
	v_mfma_f32_16x16x32_bf16 v[142:145], v[242:245], v[166:169], v[142:145]
	v_mfma_f32_16x16x32_bf16 v[158:161], v[242:245], v[182:185], v[158:161]
	s_waitcnt lgkmcnt(1)
	v_mfma_f32_16x16x32_bf16 v[142:145], v[246:249], v[170:173], v[142:145]
	v_mfma_f32_16x16x32_bf16 v[158:161], v[246:249], v[186:189], v[158:161]
	s_waitcnt lgkmcnt(0)
	v_mfma_f32_16x16x32_bf16 v[142:145], v[252:255], v[174:177], v[142:145]
	v_mfma_f32_16x16x32_bf16 v[158:161], v[252:255], v[190:193], v[158:161]
	s_sub_i32 s40, s60, 64
	s_cmp_le_i32 s40, s4
	s_cbranch_scc1 .Ld16c_nma0
	v_cmp_gt_i32_e64 s[74:75], 0, v233
	v_cmp_gt_i32_e64 s[76:77], 1, v233
	v_cmp_gt_i32_e64 s[78:79], 2, v233
	v_cmp_gt_i32_e64 s[80:81], 3, v233
	v_cndmask_b32_e64 v130, v130, v230, s[74:75]
	v_cndmask_b32_e64 v131, v131, v230, s[76:77]
	v_cndmask_b32_e64 v132, v132, v230, s[78:79]
	v_cndmask_b32_e64 v133, v133, v230, s[80:81]
	v_cmp_gt_i32_e64 s[74:75], 16, v233
	v_cmp_gt_i32_e64 s[76:77], 17, v233
	v_cmp_gt_i32_e64 s[78:79], 18, v233
	v_cmp_gt_i32_e64 s[80:81], 19, v233
	v_cndmask_b32_e64 v134, v134, v230, s[74:75]
	v_cndmask_b32_e64 v135, v135, v230, s[76:77]
	v_cndmask_b32_e64 v136, v136, v230, s[78:79]
	v_cndmask_b32_e64 v137, v137, v230, s[80:81]
	v_cmp_gt_i32_e64 s[74:75], 32, v233
	v_cmp_gt_i32_e64 s[76:77], 33, v233
	v_cmp_gt_i32_e64 s[78:79], 34, v233
	v_cmp_gt_i32_e64 s[80:81], 35, v233
	v_cndmask_b32_e64 v138, v138, v230, s[74:75]
	v_cndmask_b32_e64 v139, v139, v230, s[76:77]
	v_cndmask_b32_e64 v140, v140, v230, s[78:79]
	v_cndmask_b32_e64 v141, v141, v230, s[80:81]
	v_cmp_gt_i32_e64 s[74:75], 48, v233
	v_cmp_gt_i32_e64 s[76:77], 49, v233
	v_cmp_gt_i32_e64 s[78:79], 50, v233
	v_cmp_gt_i32_e64 s[80:81], 51, v233
	v_cndmask_b32_e64 v142, v142, v230, s[74:75]
	v_cndmask_b32_e64 v143, v143, v230, s[76:77]
	v_cndmask_b32_e64 v144, v144, v230, s[78:79]
	v_cndmask_b32_e64 v145, v145, v230, s[80:81]
	v_cmp_gt_i32_e64 s[74:75], -16, v233
	v_cmp_gt_i32_e64 s[76:77], -15, v233
	v_cmp_gt_i32_e64 s[78:79], -14, v233
	v_cmp_gt_i32_e64 s[80:81], -13, v233
	v_cndmask_b32_e64 v146, v146, v230, s[74:75]
	v_cndmask_b32_e64 v147, v147, v230, s[76:77]
	v_cndmask_b32_e64 v148, v148, v230, s[78:79]
	v_cndmask_b32_e64 v149, v149, v230, s[80:81]
	v_cmp_gt_i32_e64 s[74:75], 0, v233
	v_cmp_gt_i32_e64 s[76:77], 1, v233
	v_cmp_gt_i32_e64 s[78:79], 2, v233
	v_cmp_gt_i32_e64 s[80:81], 3, v233
	v_cndmask_b32_e64 v150, v150, v230, s[74:75]
	v_cndmask_b32_e64 v151, v151, v230, s[76:77]
	v_cndmask_b32_e64 v152, v152, v230, s[78:79]
	v_cndmask_b32_e64 v153, v153, v230, s[80:81]
	v_cmp_gt_i32_e64 s[74:75], 16, v233
	v_cmp_gt_i32_e64 s[76:77], 17, v233
	v_cmp_gt_i32_e64 s[78:79], 18, v233
	v_cmp_gt_i32_e64 s[80:81], 19, v233
	v_cndmask_b32_e64 v154, v154, v230, s[74:75]
	v_cndmask_b32_e64 v155, v155, v230, s[76:77]
	v_cndmask_b32_e64 v156, v156, v230, s[78:79]
	v_cndmask_b32_e64 v157, v157, v230, s[80:81]
	v_cmp_gt_i32_e64 s[74:75], 32, v233
	v_cmp_gt_i32_e64 s[76:77], 33, v233
	v_cmp_gt_i32_e64 s[78:79], 34, v233
	v_cmp_gt_i32_e64 s[80:81], 35, v233
	v_cndmask_b32_e64 v158, v158, v230, s[74:75]
	v_cndmask_b32_e64 v159, v159, v230, s[76:77]
	v_cndmask_b32_e64 v160, v160, v230, s[78:79]
	v_cndmask_b32_e64 v161, v161, v230, s[80:81]

.LBB0_2418:
	s_sub_i32 s73, s60, 94
	s_cmp_gt_i32 s73, s4
	s_cbranch_scc1 .Ld16c_end1
	ds_read_b128 v[252:255], v219 offset:16512
	s_waitcnt lgkmcnt(3)
	v_mfma_f32_16x16x32_bf16 v[130:133], v[238:241], v[162:165], 0
	v_mfma_f32_16x16x32_bf16 v[146:149], v[238:241], v[178:181], 0
	ds_read_b128 v[238:241], v218 offset:20480
	s_waitcnt lgkmcnt(3)
	v_mfma_f32_16x16x32_bf16 v[130:133], v[242:245], v[166:169], v[130:133]
	v_mfma_f32_16x16x32_bf16 v[146:149], v[242:245], v[182:185], v[146:149]
	ds_read_b128 v[242:245], v219 offset:20480
	s_waitcnt lgkmcnt(3)
	v_mfma_f32_16x16x32_bf16 v[130:133], v[246:249], v[170:173], v[130:133]
	v_mfma_f32_16x16x32_bf16 v[146:149], v[246:249], v[186:189], v[146:149]
	ds_read_b128 v[246:249], v218 offset:20608
	s_waitcnt lgkmcnt(3)
	v_mfma_f32_16x16x32_bf16 v[130:133], v[252:255], v[174:177], v[130:133]
	v_mfma_f32_16x16x32_bf16 v[146:149], v[252:255], v[190:193], v[146:149]
	ds_read_b128 v[252:255], v219 offset:20608
	s_waitcnt lgkmcnt(3)
	v_mfma_f32_16x16x32_bf16 v[134:137], v[238:241], v[162:165], 0
	v_mfma_f32_16x16x32_bf16 v[150:153], v[238:241], v[178:181], 0
	ds_read_b128 v[238:241], v218 offset:24576
	s_waitcnt lgkmcnt(3)
	v_mfma_f32_16x16x32_bf16 v[134:137], v[242:245], v[166:169], v[134:137]
	v_mfma_f32_16x16x32_bf16 v[150:153], v[242:245], v[182:185], v[150:153]
	ds_read_b128 v[242:245], v219 offset:24576
	s_waitcnt lgkmcnt(3)
	v_mfma_f32_16x16x32_bf16 v[134:137], v[246:249], v[170:173], v[134:137]
	v_mfma_f32_16x16x32_bf16 v[150:153], v[246:249], v[186:189], v[150:153]
	ds_read_b128 v[246:249], v218 offset:24704
	s_waitcnt lgkmcnt(3)
	v_mfma_f32_16x16x32_bf16 v[134:137], v[252:255], v[174:177], v[134:137]
	v_mfma_f32_16x16x32_bf16 v[150:153], v[252:255], v[190:193], v[150:153]
	ds_read_b128 v[252:255], v219 offset:24704
	s_waitcnt lgkmcnt(3)
	v_mfma_f32_16x16x32_bf16 v[138:141], v[238:241], v[162:165], 0
	v_mfma_f32_16x16x32_bf16 v[154:157], v[238:241], v[178:181], 0
	ds_read_b128 v[238:241], v218 offset:28672
	s_waitcnt lgkmcnt(3)
	v_mfma_f32_16x16x32_bf16 v[138:141], v[242:245], v[166:169], v[138:141]
	v_mfma_f32_16x16x32_bf16 v[154:157], v[242:245], v[182:185], v[154:157]
	ds_read_b128 v[242:245], v219 offset:28672
	s_waitcnt lgkmcnt(3)
	v_mfma_f32_16x16x32_bf16 v[138:141], v[246:249], v[170:173], v[138:141]
	v_mfma_f32_16x16x32_bf16 v[154:157], v[246:249], v[186:189], v[154:157]
	ds_read_b128 v[246:249], v218 offset:28800
	s_waitcnt lgkmcnt(3)
	v_mfma_f32_16x16x32_bf16 v[138:141], v[252:255], v[174:177], v[138:141]
	v_mfma_f32_16x16x32_bf16 v[154:157], v[252:255], v[190:193], v[154:157]
	ds_read_b128 v[252:255], v219 offset:28800
	s_waitcnt lgkmcnt(3)
	v_mfma_f32_16x16x32_bf16 v[142:145], v[238:241], v[162:165], 0
	v_mfma_f32_16x16x32_bf16 v[158:161], v[238:241], v[178:181], 0
	s_waitcnt lgkmcnt(2)
	v_mfma_f32_16x16x32_bf16 v[142:145], v[242:245], v[166:169], v[142:145]
	v_mfma_f32_16x16x32_bf16 v[158:161], v[242:245], v[182:185], v[158:161]
	s_waitcnt lgkmcnt(1)
	v_mfma_f32_16x16x32_bf16 v[142:145], v[246:249], v[170:173], v[142:145]
	v_mfma_f32_16x16x32_bf16 v[158:161], v[246:249], v[186:189], v[158:161]
	s_waitcnt lgkmcnt(0)
	v_mfma_f32_16x16x32_bf16 v[142:145], v[252:255], v[174:177], v[142:145]
	v_mfma_f32_16x16x32_bf16 v[158:161], v[252:255], v[190:193], v[158:161]
	s_cmp_le_i32 s60, s4
	s_cbranch_scc1 .Ld16c_nma1
	v_subrev_u32_e32 v246, 64, v233
	v_cmp_gt_i32_e64 s[74:75], 0, v246
	v_cmp_gt_i32_e64 s[76:77], 1, v246
	v_cmp_gt_i32_e64 s[78:79], 2, v246
	v_cmp_gt_i32_e64 s[80:81], 3, v246
	v_cndmask_b32_e64 v130, v130, v230, s[74:75]
	v_cndmask_b32_e64 v131, v131, v230, s[76:77]
	v_cndmask_b32_e64 v132, v132, v230, s[78:79]
	v_cndmask_b32_e64 v133, v133, v230, s[80:81]
	v_cmp_gt_i32_e64 s[74:75], 16, v246
	v_cmp_gt_i32_e64 s[76:77], 17, v246
	v_cmp_gt_i32_e64 s[78:79], 18, v246
	v_cmp_gt_i32_e64 s[80:81], 19, v246
	v_cndmask_b32_e64 v134, v134, v230, s[74:75]
	v_cndmask_b32_e64 v135, v135, v230, s[76:77]
	v_cndmask_b32_e64 v136, v136, v230, s[78:79]
	v_cndmask_b32_e64 v137, v137, v230, s[80:81]
	v_cmp_gt_i32_e64 s[74:75], 32, v246
	v_cmp_gt_i32_e64 s[76:77], 33, v246
	v_cmp_gt_i32_e64 s[78:79], 34, v246
	v_cmp_gt_i32_e64 s[80:81], 35, v246
	v_cndmask_b32_e64 v138, v138, v230, s[74:75]
	v_cndmask_b32_e64 v139, v139, v230, s[76:77]
	v_cndmask_b32_e64 v140, v140, v230, s[78:79]
	v_cndmask_b32_e64 v141, v141, v230, s[80:81]
	v_cmp_gt_i32_e64 s[74:75], 48, v246
	v_cmp_gt_i32_e64 s[76:77], 49, v246
	v_cmp_gt_i32_e64 s[78:79], 50, v246
	v_cmp_gt_i32_e64 s[80:81], 51, v246
	v_cndmask_b32_e64 v142, v142, v230, s[74:75]
	v_cndmask_b32_e64 v143, v143, v230, s[76:77]
	v_cndmask_b32_e64 v144, v144, v230, s[78:79]
	v_cndmask_b32_e64 v145, v145, v230, s[80:81]
	v_cmp_gt_i32_e64 s[74:75], -16, v246
	v_cmp_gt_i32_e64 s[76:77], -15, v246
	v_cmp_gt_i32_e64 s[78:79], -14, v246
	v_cmp_gt_i32_e64 s[80:81], -13, v246
	v_cndmask_b32_e64 v146, v146, v230, s[74:75]
	v_cndmask_b32_e64 v147, v147, v230, s[76:77]
	v_cndmask_b32_e64 v148, v148, v230, s[78:79]
	v_cndmask_b32_e64 v149, v149, v230, s[80:81]
	v_cmp_gt_i32_e64 s[74:75], 0, v246
	v_cmp_gt_i32_e64 s[76:77], 1, v246
	v_cmp_gt_i32_e64 s[78:79], 2, v246
	v_cmp_gt_i32_e64 s[80:81], 3, v246
	v_cndmask_b32_e64 v150, v150, v230, s[74:75]
	v_cndmask_b32_e64 v151, v151, v230, s[76:77]
	v_cndmask_b32_e64 v152, v152, v230, s[78:79]
	v_cndmask_b32_e64 v153, v153, v230, s[80:81]
	v_cmp_gt_i32_e64 s[74:75], 16, v246
	v_cmp_gt_i32_e64 s[76:77], 17, v246
	v_cmp_gt_i32_e64 s[78:79], 18, v246
	v_cmp_gt_i32_e64 s[80:81], 19, v246
	v_cndmask_b32_e64 v154, v154, v230, s[74:75]
	v_cndmask_b32_e64 v155, v155, v230, s[76:77]
	v_cndmask_b32_e64 v156, v156, v230, s[78:79]
	v_cndmask_b32_e64 v157, v157, v230, s[80:81]
	v_cmp_gt_i32_e64 s[74:75], 32, v246
	v_cmp_gt_i32_e64 s[76:77], 33, v246
	v_cmp_gt_i32_e64 s[78:79], 34, v246
	v_cmp_gt_i32_e64 s[80:81], 35, v246
	v_cndmask_b32_e64 v158, v158, v230, s[74:75]
	v_cndmask_b32_e64 v159, v159, v230, s[76:77]
	v_cndmask_b32_e64 v160, v160, v230, s[78:79]
	v_cndmask_b32_e64 v161, v161, v230, s[80:81]
